# rotated phaseA order with 5 unclaimed owner passes
# baseline (speedup 1.0000x reference)
;     ...
;     for (int pass = 0; pass * NWAVE < NU; ++pass) {
;         const int unit = pass * NWAVE + wave;
;         const bool active = unit < NU;
;         const int ucl = active ? unit : NU - 1;
.Lha_c_w:
	s_barrier
	ds_read_b32 v3, v2
	s_waitcnt lgkmcnt(0)
	v_readfirstlane_b32 s88, v3
	s_nop 3
	s_add_u32 s88, s88, 5
	s_cmp_ge_u32 s88, 9
	s_cbranch_scc1 .Lha_next
	s_add_u32 s6, s88, 4
	s_cmp_ge_u32 s6, 9
	s_cselect_b32 s7, 9, 0
	s_sub_u32 s6, s6, s7
	s_lshl_b32 s2, s6, 3
	v_add_u32_e32 v232, s2, v223
